# also out-projection GEMM second round as 256 half tiles; FFN weight conversion afterwards spread over all workgroups
# speedup vs baseline: 1.0125x; 1.0007x over previous
.LBB0_342:
	v_lshlrev_b64 v[152:153], 2, v[152:153]
	v_lshl_add_u64 v[158:159], s[8:9], 0, v[158:159]
	v_lshl_add_u64 v[154:155], v[156:157], 0, v[152:153]
	v_lshl_add_u64 v[152:153], v[158:159], 0, v[152:153]
	global_load_dwordx4 v[156:159], v[154:155], off offset:16
	global_load_dwordx4 v[176:179], v[154:155], off
	global_load_dwordx4 v[180:183], v[154:155], off offset:144
	global_load_dwordx4 v[184:187], v[154:155], off offset:128
	s_mov_b64 s[20:21], 0x10000
	v_add_co_u32_e32 v196, vcc, 0x10000, v154
	v_lshl_add_u64 v[192:193], v[154:155], 0, s[20:21]
	s_nop 0
	v_addc_co_u32_e32 v197, vcc, 0, v155, vcc
	global_load_dwordx4 v[188:191], v[196:197], off
	s_nop 0
	global_load_dwordx4 v[192:195], v[192:193], off offset:16
	s_mov_b64 s[20:21], 0x10080
	v_lshl_add_u64 v[200:201], v[154:155], 0, s[20:21]
	global_load_dwordx4 v[196:199], v[196:197], off offset:128
	s_nop 0
	global_load_dwordx4 v[230:233], v[200:201], off offset:16
	s_mov_b32 s13, 0x10000
	s_mov_b64 s[20:21], 0x20000
	s_mov_b32 s15, 0x90000
	s_mov_b64 s[24:25], s[18:19]
	s_mov_b64 s[22:23], s[16:17]
	s_waitcnt vmcnt(0)
	v_pk_fma_f32 v[138:139], v[138:139], v[102:103], v[156:157]
	v_pk_fma_f32 v[144:145], v[144:145], v[112:113], v[178:179]
	v_pk_fma_f32 v[126:127], v[126:127], v[98:99], v[180:181]
	v_pk_fma_f32 v[132:133], v[132:133], v[108:109], v[186:187]
	v_pk_fma_f32 v[130:131], v[130:131], v[106:107], v[184:185]
	global_store_dwordx4 v[152:153], v[130:133], off offset:128
	v_pk_fma_f32 v[128:129], v[128:129], v[100:101], v[182:183]
	v_pk_fma_f32 v[142:143], v[142:143], v[110:111], v[176:177]
	v_add_co_u32_e32 v130, vcc, s13, v152
	v_pk_fma_f32 v[122:123], v[122:123], v[102:103], v[192:193]
	s_nop 0
	v_addc_co_u32_e32 v131, vcc, 0, v153, vcc
	v_pk_fma_f32 v[124:125], v[124:125], v[104:105], v[194:195]
	s_mov_b32 s13, 0x20000
	v_pk_fma_f32 v[140:141], v[140:141], v[104:105], v[158:159]
	global_store_dwordx4 v[152:153], v[126:129], off offset:144
	global_store_dwordx4 v[130:131], v[122:125], off offset:16
	v_pk_fma_f32 v[120:121], v[120:121], v[108:109], v[198:199]
	v_pk_fma_f32 v[128:129], v[136:137], v[112:113], v[190:191]
	v_pk_fma_f32 v[126:127], v[134:135], v[110:111], v[188:189]
	v_pk_fma_f32 v[118:119], v[118:119], v[106:107], v[196:197]
	v_pk_fma_f32 v[114:115], v[114:115], v[98:99], v[230:231]
	v_pk_fma_f32 v[116:117], v[116:117], v[100:101], v[232:233]
	v_add_co_u32_e32 v122, vcc, s13, v154
	global_store_dwordx4 v[152:153], v[142:145], off
	global_store_dwordx4 v[152:153], v[138:141], off offset:16
	global_store_dwordx4 v[130:131], v[126:129], off
	global_store_dwordx4 v[130:131], v[118:121], off offset:128
	global_store_dwordx4 v[130:131], v[114:117], off offset:144
	v_addc_co_u32_e32 v123, vcc, 0, v155, vcc
	v_lshl_add_u64 v[118:119], v[154:155], 0, s[20:21]
	s_mov_b64 s[20:21], 0x20080
	global_load_dwordx4 v[114:117], v[122:123], off
	s_nop 0
	global_load_dwordx4 v[118:121], v[118:119], off offset:16
	v_lshl_add_u64 v[126:127], v[154:155], 0, s[20:21]
	s_mov_b64 s[20:21], 0x30000
	v_add_co_u32_e32 v138, vcc, s94, v154
	global_load_dwordx4 v[122:125], v[122:123], off offset:128
	s_nop 0
	global_load_dwordx4 v[126:129], v[126:127], off offset:16
	v_lshl_add_u64 v[134:135], v[154:155], 0, s[20:21]
	v_addc_co_u32_e32 v139, vcc, 0, v155, vcc
	s_mov_b64 s[20:21], 0x30080
	global_load_dwordx4 v[130:133], v[138:139], off
	s_nop 0
	global_load_dwordx4 v[134:137], v[134:135], off offset:16
	v_lshl_add_u64 v[142:143], v[154:155], 0, s[20:21]
	global_load_dwordx4 v[138:141], v[138:139], off offset:128
	s_nop 0
	global_load_dwordx4 v[142:145], v[142:143], off offset:16
	s_mov_b64 s[20:21], 0x80000
	s_waitcnt vmcnt(0)
	v_pk_fma_f32 v[94:95], v[94:95], v[110:111], v[114:115]
	v_add_co_u32_e32 v114, vcc, s13, v152
	s_mov_b32 s13, 0x80000
	s_nop 0
	v_addc_co_u32_e32 v115, vcc, 0, v153, vcc
	v_pk_fma_f32 v[84:85], v[84:85], v[108:109], v[124:125]
	v_pk_fma_f32 v[82:83], v[82:83], v[106:107], v[122:123]
	global_store_dwordx4 v[114:115], v[82:85], off offset:128
	v_pk_fma_f32 v[78:79], v[78:79], v[98:99], v[126:127]
	v_pk_fma_f32 v[80:81], v[80:81], v[100:101], v[128:129]
	v_add_co_u32_e32 v82, vcc, s94, v152
	v_pk_fma_f32 v[74:75], v[74:75], v[102:103], v[134:135]
	s_nop 0
	v_addc_co_u32_e32 v83, vcc, 0, v153, vcc
	v_pk_fma_f32 v[76:77], v[76:77], v[104:105], v[136:137]
	v_pk_fma_f32 v[96:97], v[96:97], v[112:113], v[116:117]
	v_pk_fma_f32 v[90:91], v[90:91], v[102:103], v[118:119]
	v_pk_fma_f32 v[92:93], v[92:93], v[104:105], v[120:121]
	global_store_dwordx4 v[114:115], v[78:81], off offset:144
	global_store_dwordx4 v[82:83], v[74:77], off offset:16
	v_pk_fma_f32 v[72:73], v[72:73], v[108:109], v[140:141]
	v_pk_fma_f32 v[80:81], v[88:89], v[112:113], v[132:133]
	v_pk_fma_f32 v[78:79], v[86:87], v[110:111], v[130:131]
	v_pk_fma_f32 v[70:71], v[70:71], v[106:107], v[138:139]
	v_pk_fma_f32 v[66:67], v[66:67], v[98:99], v[142:143]
	v_pk_fma_f32 v[68:69], v[68:69], v[100:101], v[144:145]
	v_add_co_u32_e32 v74, vcc, s13, v154
	global_store_dwordx4 v[114:115], v[94:97], off
	global_store_dwordx4 v[114:115], v[90:93], off offset:16
	global_store_dwordx4 v[82:83], v[78:81], off
	global_store_dwordx4 v[82:83], v[70:73], off offset:128
	global_store_dwordx4 v[82:83], v[66:69], off offset:144
	s_cmp_lg_u32 s99, 0
	s_cbranch_scc1 .Lop_half_done
	v_addc_co_u32_e32 v75, vcc, 0, v155, vcc
	v_lshl_add_u64 v[70:71], v[154:155], 0, s[20:21]
	s_mov_b64 s[20:21], 0x80080
	global_load_dwordx4 v[66:69], v[74:75], off
	s_nop 0
	global_load_dwordx4 v[70:73], v[70:71], off offset:16
	v_lshl_add_u64 v[78:79], v[154:155], 0, s[20:21]
	s_mov_b64 s[20:21], 0x90000
	v_add_co_u32_e32 v90, vcc, s15, v154
	global_load_dwordx4 v[74:77], v[74:75], off offset:128
	s_nop 0
	global_load_dwordx4 v[78:81], v[78:79], off offset:16
	v_lshl_add_u64 v[86:87], v[154:155], 0, s[20:21]
	v_addc_co_u32_e32 v91, vcc, 0, v155, vcc
	s_mov_b64 s[20:21], 0x90080
	global_load_dwordx4 v[82:85], v[90:91], off
	s_nop 0
	global_load_dwordx4 v[86:89], v[86:87], off offset:16
	v_lshl_add_u64 v[94:95], v[154:155], 0, s[20:21]
	global_load_dwordx4 v[90:93], v[90:91], off offset:128
	s_nop 0
	global_load_dwordx4 v[94:97], v[94:95], off offset:16
	s_mov_b64 s[20:21], 0xa0000
	s_waitcnt vmcnt(0)
	v_pk_fma_f32 v[62:63], v[62:63], v[110:111], v[66:67]
	v_add_co_u32_e32 v66, vcc, s13, v152
	s_mov_b32 s13, 0xa0000
	s_nop 0
	v_addc_co_u32_e32 v67, vcc, 0, v153, vcc
	v_pk_fma_f32 v[52:53], v[52:53], v[108:109], v[76:77]
	v_pk_fma_f32 v[50:51], v[50:51], v[106:107], v[74:75]
	global_store_dwordx4 v[66:67], v[50:53], off offset:128
	v_pk_fma_f32 v[46:47], v[46:47], v[98:99], v[78:79]
	v_pk_fma_f32 v[48:49], v[48:49], v[100:101], v[80:81]
	v_add_co_u32_e32 v50, vcc, s15, v152
	v_pk_fma_f32 v[42:43], v[42:43], v[102:103], v[86:87]
	s_nop 0
	v_addc_co_u32_e32 v51, vcc, 0, v153, vcc
	v_pk_fma_f32 v[44:45], v[44:45], v[104:105], v[88:89]
	v_pk_fma_f32 v[64:65], v[64:65], v[112:113], v[68:69]
	v_pk_fma_f32 v[58:59], v[58:59], v[102:103], v[70:71]
	v_pk_fma_f32 v[60:61], v[60:61], v[104:105], v[72:73]
	global_store_dwordx4 v[66:67], v[46:49], off offset:144
	global_store_dwordx4 v[50:51], v[42:45], off offset:16
	v_pk_fma_f32 v[40:41], v[40:41], v[108:109], v[92:93]
	v_pk_fma_f32 v[48:49], v[56:57], v[112:113], v[84:85]
	v_pk_fma_f32 v[46:47], v[54:55], v[110:111], v[82:83]
	v_pk_fma_f32 v[38:39], v[38:39], v[106:107], v[90:91]
	v_pk_fma_f32 v[34:35], v[34:35], v[98:99], v[94:95]
	v_pk_fma_f32 v[36:37], v[36:37], v[100:101], v[96:97]
	v_add_co_u32_e32 v42, vcc, s13, v154
	global_store_dwordx4 v[66:67], v[62:65], off
	global_store_dwordx4 v[66:67], v[58:61], off offset:16
	global_store_dwordx4 v[50:51], v[46:49], off
	global_store_dwordx4 v[50:51], v[38:41], off offset:128
	global_store_dwordx4 v[50:51], v[34:37], off offset:144
	v_addc_co_u32_e32 v43, vcc, 0, v155, vcc
	v_lshl_add_u64 v[38:39], v[154:155], 0, s[20:21]
	s_mov_b64 s[20:21], 0xa0080
	global_load_dwordx4 v[34:37], v[42:43], off
	s_nop 0
	global_load_dwordx4 v[38:41], v[38:39], off offset:16
	v_lshl_add_u64 v[46:47], v[154:155], 0, s[20:21]
	s_mov_b64 s[20:21], 0xb0000
	s_mov_b32 s15, 0xb0000
	global_load_dwordx4 v[42:45], v[42:43], off offset:128
	s_nop 0
	global_load_dwordx4 v[46:49], v[46:47], off offset:16
	v_lshl_add_u64 v[54:55], v[154:155], 0, s[20:21]
	v_add_co_u32_e32 v58, vcc, s15, v154
	s_mov_b64 s[20:21], 0xb0080
	s_nop 0
	v_addc_co_u32_e32 v59, vcc, 0, v155, vcc
	v_lshl_add_u64 v[62:63], v[154:155], 0, s[20:21]
	global_load_dwordx4 v[50:53], v[58:59], off
	s_nop 0
	global_load_dwordx4 v[54:57], v[54:55], off offset:16
	s_nop 0
	global_load_dwordx4 v[58:61], v[58:59], off offset:128
	s_nop 0
	global_load_dwordx4 v[62:65], v[62:63], off offset:16
	s_mov_b32 s21, s12
	s_mov_b32 s20, s14
	s_waitcnt vmcnt(0)
	v_pk_fma_f32 v[30:31], v[30:31], v[110:111], v[34:35]
	v_add_co_u32_e32 v34, vcc, s13, v152
	v_pk_fma_f32 v[32:33], v[32:33], v[112:113], v[36:37]
	s_nop 0
	v_addc_co_u32_e32 v35, vcc, 0, v153, vcc
	v_pk_fma_f32 v[16:17], v[16:17], v[108:109], v[44:45]
	v_pk_fma_f32 v[14:15], v[14:15], v[106:107], v[42:43]
	global_store_dwordx4 v[34:35], v[14:17], off offset:128
	v_pk_fma_f32 v[10:11], v[10:11], v[98:99], v[46:47]
	v_pk_fma_f32 v[12:13], v[12:13], v[100:101], v[48:49]
	v_add_co_u32_e32 v14, vcc, s15, v152
	global_store_dwordx4 v[34:35], v[10:13], off offset:144
	s_nop 0
	v_addc_co_u32_e32 v15, vcc, 0, v153, vcc
	v_pk_fma_f32 v[12:13], v[24:25], v[112:113], v[52:53]
	v_pk_fma_f32 v[10:11], v[22:23], v[110:111], v[50:51]
	v_pk_fma_f32 v[26:27], v[26:27], v[102:103], v[38:39]
	v_pk_fma_f32 v[28:29], v[28:29], v[104:105], v[40:41]
	global_store_dwordx4 v[14:15], v[10:13], off
	v_pk_fma_f32 v[8:9], v[8:9], v[108:109], v[60:61]
	v_pk_fma_f32 v[6:7], v[6:7], v[106:107], v[58:59]
	v_pk_fma_f32 v[10:11], v[18:19], v[102:103], v[54:55]
	v_pk_fma_f32 v[12:13], v[20:21], v[104:105], v[56:57]
	v_pk_fma_f32 v[2:3], v[2:3], v[98:99], v[62:63]
	v_pk_fma_f32 v[4:5], v[4:5], v[100:101], v[64:65]
	s_and_b64 vcc, exec, s[4:5]
	global_store_dwordx4 v[34:35], v[30:33], off
	global_store_dwordx4 v[34:35], v[26:29], off offset:16
	global_store_dwordx4 v[14:15], v[10:13], off offset:16
	global_store_dwordx4 v[14:15], v[6:9], off offset:128
	global_store_dwordx4 v[14:15], v[2:5], off offset:144
	s_cbranch_vccnz .LBB0_351
	s_branch .LBB0_343
.Lop_half_done:
	s_mov_b32 s21, s12
	s_mov_b32 s20, s14
	s_and_b64 vcc, exec, s[4:5]
	s_cbranch_vccnz .LBB0_351
.LBB0_343:
	s_add_i32 s44, s44, 1
	s_mul_i32 s4, s44, s43
	s_mul_hi_u32 s5, s44, s0
	s_add_i32 s5, s5, s4
	s_mul_i32 s4, s44, s0
	v_readlane_b32 s99, v255, 41
	s_cmp_eq_u32 s44, 1
	s_cselect_b32 s99, s99, 0
	s_lshr_b32 s98, s1, s99
	s_add_u32 s16, s4, s98
	s_addc_u32 s17, s5, s34
	v_cmp_gt_i64_e64 s[4:5], s[16:17], v[164:165]
	s_and_b64 vcc, exec, s[4:5]
	s_cbranch_vccnz .LBB0_345
	s_ashr_i32 s12, s16, 31
	s_lshr_b32 s12, s12, 29
	s_add_i32 s12, s16, s12
	s_ashr_i32 s13, s12, 3
	s_and_b32 s12, s12, -8
	s_sub_i32 s12, s16, s12
	s_cmp_lt_i32 s12, 0
	s_cselect_b32 s14, 49, 48
	s_mul_i32 s12, s14, s12
	s_add_i32 s12, s12, s13
	s_ashr_i32 s13, s12, 31
	s_lshr_b32 s13, s13, 28
	s_add_i32 s13, s12, s13
	s_ashr_i32 s14, s13, 4
	s_lshl_b32 s14, s14, 2
	s_sub_i32 s15, 0x60, s14
	s_min_i32 s15, s15, 4
	s_abs_i32 s18, s15
	v_cvt_f32_u32_e32 v2, s18
	s_sub_i32 s26, 0, s18
	s_and_b32 s13, s13, -16
	s_sub_i32 s13, s12, s13
	v_rcp_iflag_f32_e32 v2, v2
	s_abs_i32 s12, s13
	s_xor_b32 s19, s13, s15
	s_ashr_i32 s19, s19, 31
	v_mul_f32_e32 v2, 0x4f7ffffe, v2
	v_cvt_u32_f32_e32 v2, v2
	s_nop 0
	v_readfirstlane_b32 s27, v2
	s_mul_i32 s26, s26, s27
	s_mul_hi_u32 s26, s27, s26
	s_add_i32 s27, s27, s26
	s_mul_hi_u32 s26, s12, s27
	s_mul_i32 s27, s26, s18
	s_sub_i32 s12, s12, s27
	s_add_i32 s28, s26, 1
	s_sub_i32 s27, s12, s18
	s_cmp_ge_u32 s12, s18
	s_cselect_b32 s26, s28, s26
	s_cselect_b32 s12, s27, s12
	s_add_i32 s27, s26, 1
	s_cmp_ge_u32 s12, s18
	s_cselect_b32 s12, s27, s26
	s_xor_b32 s12, s12, s19
	s_sub_i32 s12, s12, s19
	s_mul_i32 s15, s12, s15
	s_sub_i32 s13, s13, s15
	s_add_i32 s14, s13, s14
.LBB0_345:
	s_ashr_i32 s15, s14, 31
	v_cmp_lt_i64_e32 vcc, s[16:17], v[166:167]
	s_lshl_b64 s[16:17], s[14:15], 19
	v_readlane_b32 s18, v254, 33
	v_readlane_b32 s19, v254, 34
	s_add_u32 s16, s18, s16
	s_addc_u32 s17, s19, s17
	v_readlane_b32 s98, v255, 41
	v_readlane_b32 s99, v254, 0
	s_and_b32 s99, s99, s98
	s_mul_i32 s99, s99, 0x40000
	s_add_u32 s16, s16, s99
	s_addc_u32 s17, s17, 0
	s_and_b64 s[18:19], vcc, exec
	s_cselect_b32 s15, s17, s23
	s_cselect_b32 s45, s16, s22
	s_ashr_i32 s13, s12, 31
	s_lshl_b64 s[18:19], s[12:13], 19
	s_add_u32 s18, s3, s18
	s_addc_u32 s19, s30, s19
	s_and_b64 s[26:27], vcc, exec
	s_cselect_b32 s13, s19, s25
	s_cselect_b32 s46, s18, s24
	s_add_u32 s47, s24, 0x100
	v_mov_b32_e32 v2, 0
	s_addc_u32 s48, s25, 0
	s_mov_b32 s49, -2
	v_mov_b32_e32 v3, v2
	v_mov_b32_e32 v4, v2
	v_mov_b32_e32 v5, v2
	v_mov_b32_e32 v6, v2
	v_mov_b32_e32 v7, v2
	v_mov_b32_e32 v8, v2
	v_mov_b32_e32 v9, v2
	v_mov_b32_e32 v10, v2
	v_mov_b32_e32 v11, v2
	v_mov_b32_e32 v12, v2
	v_mov_b32_e32 v13, v2
	v_mov_b32_e32 v14, v2
	v_mov_b32_e32 v15, v2
	v_mov_b32_e32 v16, v2
	v_mov_b32_e32 v17, v2
	v_mov_b32_e32 v34, v2
	v_mov_b32_e32 v35, v2
	v_mov_b32_e32 v36, v2
	v_mov_b32_e32 v37, v2
	v_mov_b32_e32 v38, v2
	v_mov_b32_e32 v39, v2
	v_mov_b32_e32 v40, v2
	v_mov_b32_e32 v41, v2
	v_mov_b32_e32 v46, v2
	v_mov_b32_e32 v47, v2
	v_mov_b32_e32 v48, v2
	v_mov_b32_e32 v49, v2
	v_mov_b32_e32 v50, v2
	v_mov_b32_e32 v51, v2
	v_mov_b32_e32 v52, v2
	v_mov_b32_e32 v53, v2
	v_mov_b32_e32 v18, v2
	v_mov_b32_e32 v19, v2
	v_mov_b32_e32 v20, v2
	v_mov_b32_e32 v21, v2
	v_mov_b32_e32 v22, v2
	v_mov_b32_e32 v23, v2
	v_mov_b32_e32 v24, v2
	v_mov_b32_e32 v25, v2
	v_mov_b32_e32 v26, v2
	v_mov_b32_e32 v27, v2
	v_mov_b32_e32 v28, v2
	v_mov_b32_e32 v29, v2
	v_mov_b32_e32 v30, v2
	v_mov_b32_e32 v31, v2
	v_mov_b32_e32 v32, v2
	v_mov_b32_e32 v33, v2
	v_mov_b32_e32 v42, v2
	v_mov_b32_e32 v43, v2
	v_mov_b32_e32 v44, v2
	v_mov_b32_e32 v45, v2
	v_mov_b32_e32 v54, v2
	v_mov_b32_e32 v55, v2
	v_mov_b32_e32 v56, v2
	v_mov_b32_e32 v57, v2
	v_mov_b32_e32 v58, v2
	v_mov_b32_e32 v59, v2
	v_mov_b32_e32 v60, v2
	v_mov_b32_e32 v61, v2
	v_mov_b32_e32 v62, v2
	v_mov_b32_e32 v63, v2
	v_mov_b32_e32 v64, v2
	v_mov_b32_e32 v65, v2
	v_mov_b32_e32 v66, v2
	v_mov_b32_e32 v67, v2
	v_mov_b32_e32 v68, v2
	v_mov_b32_e32 v69, v2
	v_mov_b32_e32 v70, v2
	v_mov_b32_e32 v71, v2
	v_mov_b32_e32 v72, v2
	v_mov_b32_e32 v73, v2
	v_mov_b32_e32 v78, v2
	v_mov_b32_e32 v79, v2
	v_mov_b32_e32 v80, v2
	v_mov_b32_e32 v81, v2
	v_mov_b32_e32 v82, v2
	v_mov_b32_e32 v83, v2
	v_mov_b32_e32 v84, v2
	v_mov_b32_e32 v85, v2
	v_mov_b32_e32 v114, v2
	v_mov_b32_e32 v115, v2
	v_mov_b32_e32 v116, v2
	v_mov_b32_e32 v117, v2
	v_mov_b32_e32 v118, v2
	v_mov_b32_e32 v119, v2
	v_mov_b32_e32 v120, v2
	v_mov_b32_e32 v121, v2
	v_mov_b32_e32 v126, v2
	v_mov_b32_e32 v127, v2
	v_mov_b32_e32 v128, v2
	v_mov_b32_e32 v129, v2
	v_mov_b32_e32 v130, v2
	v_mov_b32_e32 v131, v2
	v_mov_b32_e32 v132, v2
	v_mov_b32_e32 v133, v2
	v_mov_b32_e32 v74, v2
	v_mov_b32_e32 v75, v2
	v_mov_b32_e32 v76, v2
	v_mov_b32_e32 v77, v2
	v_mov_b32_e32 v86, v2
	v_mov_b32_e32 v87, v2
	v_mov_b32_e32 v88, v2
	v_mov_b32_e32 v89, v2
	v_mov_b32_e32 v90, v2
	v_mov_b32_e32 v91, v2
	v_mov_b32_e32 v92, v2
	v_mov_b32_e32 v93, v2
	v_mov_b32_e32 v94, v2
	v_mov_b32_e32 v95, v2
	v_mov_b32_e32 v96, v2
	v_mov_b32_e32 v97, v2
	v_mov_b32_e32 v122, v2
	v_mov_b32_e32 v123, v2
	v_mov_b32_e32 v124, v2
	v_mov_b32_e32 v125, v2
	v_mov_b32_e32 v134, v2
	v_mov_b32_e32 v135, v2
	v_mov_b32_e32 v136, v2
	v_mov_b32_e32 v137, v2
	v_mov_b32_e32 v138, v2
	v_mov_b32_e32 v139, v2
	v_mov_b32_e32 v140, v2
	v_mov_b32_e32 v141, v2
	v_mov_b32_e32 v142, v2
	v_mov_b32_e32 v143, v2
	v_mov_b32_e32 v144, v2
	v_mov_b32_e32 v145, v2
	v_readlane_b32 s99, v255, 41
	s_cmp_eq_u32 s44, 2
	s_cselect_b32 s99, s99, 0
.LBB0_346:
	s_add_u32 s24, s22, 0x100
	s_addc_u32 s25, s23, 0
	s_add_i32 s50, 0, 0x10000
	v_add_u32_e32 v110, s50, v160
	ds_read_b128 v[98:101], v110
	ds_read_b128 v[102:105], v110 offset:1024
	ds_read_b128 v[106:109], v110 offset:2048
	ds_read_b128 v[110:113], v110 offset:3072
	s_cmp_eq_u32 s49, 12
	s_cselect_b32 s29, s15, s25
	s_cselect_b32 s28, s45, s24
	s_cselect_b32 s27, s13, s48
	s_cselect_b32 s26, s46, s47
	v_lshl_add_u64 v[200:201], s[22:23], 0, v[150:151]
	s_add_i32 m0, s35, 0xc000
	ds_read_b128 v[152:155], v161
	ds_read_b128 v[156:159], v161 offset:1024
	ds_read_b128 v[176:179], v161 offset:2048
	ds_read_b128 v[180:183], v161 offset:3072
	ds_read_b128 v[184:187], v161 offset:4096
	ds_read_b128 v[188:191], v161 offset:5120
	ds_read_b128 v[192:195], v161 offset:6144
	ds_read_b128 v[196:199], v161 offset:7168
	global_load_lds_dwordx4 v[200:201], off
	v_lshl_add_u64 v[200:201], s[22:23], 0, v[148:149]
	s_add_i32 m0, s35, 0xe000
	s_nop 0
	global_load_lds_dwordx4 v[200:201], off
	s_waitcnt lgkmcnt(8)
	s_barrier
	s_waitcnt lgkmcnt(0)
	s_setprio 1
	s_waitcnt lgkmcnt(0)
	v_mfma_f32_16x16x32_bf16 v[142:145], v[98:101], v[152:155], v[142:145]
	v_mfma_f32_16x16x32_bf16 v[138:141], v[106:109], v[152:155], v[138:141]
	v_mfma_f32_16x16x32_bf16 v[134:137], v[98:101], v[176:179], v[134:137]
	v_mfma_f32_16x16x32_bf16 v[122:125], v[106:109], v[176:179], v[122:125]
	v_mfma_f32_16x16x32_bf16 v[94:97], v[98:101], v[184:187], v[94:97]
	v_mfma_f32_16x16x32_bf16 v[90:93], v[106:109], v[184:187], v[90:93]
	v_mfma_f32_16x16x32_bf16 v[86:89], v[98:101], v[192:195], v[86:89]
	v_mfma_f32_16x16x32_bf16 v[74:77], v[106:109], v[192:195], v[74:77]
	v_mfma_f32_16x16x32_bf16 v[142:145], v[102:105], v[156:159], v[142:145]
	v_mfma_f32_16x16x32_bf16 v[138:141], v[110:113], v[156:159], v[138:141]
	v_mfma_f32_16x16x32_bf16 v[134:137], v[102:105], v[180:183], v[134:137]
	v_mfma_f32_16x16x32_bf16 v[122:125], v[110:113], v[180:183], v[122:125]
	v_mfma_f32_16x16x32_bf16 v[94:97], v[102:105], v[188:191], v[94:97]
	v_mfma_f32_16x16x32_bf16 v[90:93], v[110:113], v[188:191], v[90:93]
	v_mfma_f32_16x16x32_bf16 v[86:89], v[102:105], v[196:199], v[86:89]
	v_mfma_f32_16x16x32_bf16 v[74:77], v[110:113], v[196:199], v[74:77]
	s_setprio 0
	s_barrier
	s_add_i32 s51, 0, 0x14000
	s_add_i32 s22, s50, s31
	v_add_u32_e32 v169, s51, v160
	v_lshl_add_u64 v[200:201], s[26:27], 0, v[0:1]
	s_mov_b32 m0, s22
	ds_read_b128 v[230:233], v169
	ds_read_b128 v[234:237], v169 offset:1024
	ds_read_b128 v[238:241], v169 offset:2048
	ds_read_b128 v[242:245], v169 offset:3072
	global_load_lds_dwordx4 v[200:201], off
	v_lshl_add_u64 v[246:247], s[26:27], 0, v[146:147]
	s_add_i32 m0, s22, 0x2000
	s_nop 0
	global_load_lds_dwordx4 v[246:247], off
	s_barrier
	s_waitcnt lgkmcnt(0)
	s_setprio 1
	s_waitcnt lgkmcnt(0)
	v_mfma_f32_16x16x32_bf16 v[130:133], v[230:233], v[152:155], v[130:133]
	v_mfma_f32_16x16x32_bf16 v[126:129], v[238:241], v[152:155], v[126:129]
	v_mfma_f32_16x16x32_bf16 v[118:121], v[230:233], v[176:179], v[118:121]
	v_mfma_f32_16x16x32_bf16 v[114:117], v[238:241], v[176:179], v[114:117]
	v_mfma_f32_16x16x32_bf16 v[82:85], v[230:233], v[184:187], v[82:85]
	v_mfma_f32_16x16x32_bf16 v[78:81], v[238:241], v[184:187], v[78:81]
	v_mfma_f32_16x16x32_bf16 v[70:73], v[230:233], v[192:195], v[70:73]
	v_mfma_f32_16x16x32_bf16 v[66:69], v[238:241], v[192:195], v[66:69]
	v_mfma_f32_16x16x32_bf16 v[130:133], v[234:237], v[156:159], v[130:133]
	v_mfma_f32_16x16x32_bf16 v[126:129], v[242:245], v[156:159], v[126:129]
	v_mfma_f32_16x16x32_bf16 v[118:121], v[234:237], v[180:183], v[118:121]
	v_mfma_f32_16x16x32_bf16 v[114:117], v[242:245], v[180:183], v[114:117]
	v_mfma_f32_16x16x32_bf16 v[82:85], v[234:237], v[188:191], v[82:85]
	v_mfma_f32_16x16x32_bf16 v[78:81], v[242:245], v[188:191], v[78:81]
	v_mfma_f32_16x16x32_bf16 v[70:73], v[234:237], v[196:199], v[70:73]
	v_mfma_f32_16x16x32_bf16 v[66:69], v[242:245], v[196:199], v[66:69]
	s_setprio 0
	s_mov_b32 m0, s35
	v_lshl_add_u64 v[248:249], s[28:29], 0, v[0:1]
	s_barrier
	ds_read_b128 v[152:155], v161 offset:16384
	ds_read_b128 v[156:159], v161 offset:17408
	ds_read_b128 v[176:179], v161 offset:18432
	ds_read_b128 v[180:183], v161 offset:19456
	ds_read_b128 v[184:187], v161 offset:20480
	ds_read_b128 v[188:191], v161 offset:21504
	ds_read_b128 v[192:195], v161 offset:22528
	ds_read_b128 v[196:199], v161 offset:23552
	global_load_lds_dwordx4 v[248:249], off
	v_lshl_add_u64 v[250:251], s[28:29], 0, v[146:147]
	s_mov_b32 m0, s36
	s_nop 0
	global_load_lds_dwordx4 v[250:251], off
	s_barrier
	s_waitcnt lgkmcnt(0)
	s_setprio 1
	s_waitcnt lgkmcnt(0)
	s_cmp_lg_u32 s99, 0
	s_cbranch_scc1 .Lop_skip3
	v_mfma_f32_16x16x32_bf16 v[62:65], v[98:101], v[152:155], v[62:65]
	v_mfma_f32_16x16x32_bf16 v[58:61], v[106:109], v[152:155], v[58:61]
	v_mfma_f32_16x16x32_bf16 v[54:57], v[98:101], v[176:179], v[54:57]
	v_mfma_f32_16x16x32_bf16 v[42:45], v[106:109], v[176:179], v[42:45]
	v_mfma_f32_16x16x32_bf16 v[30:33], v[98:101], v[184:187], v[30:33]
	v_mfma_f32_16x16x32_bf16 v[26:29], v[106:109], v[184:187], v[26:29]
	v_mfma_f32_16x16x32_bf16 v[22:25], v[98:101], v[192:195], v[22:25]
	v_mfma_f32_16x16x32_bf16 v[18:21], v[106:109], v[192:195], v[18:21]
	v_mfma_f32_16x16x32_bf16 v[62:65], v[102:105], v[156:159], v[62:65]
	v_mfma_f32_16x16x32_bf16 v[58:61], v[110:113], v[156:159], v[58:61]
	v_mfma_f32_16x16x32_bf16 v[54:57], v[102:105], v[180:183], v[54:57]
	v_mfma_f32_16x16x32_bf16 v[42:45], v[110:113], v[180:183], v[42:45]
	v_mfma_f32_16x16x32_bf16 v[30:33], v[102:105], v[188:191], v[30:33]
	v_mfma_f32_16x16x32_bf16 v[26:29], v[110:113], v[188:191], v[26:29]
	v_mfma_f32_16x16x32_bf16 v[22:25], v[102:105], v[196:199], v[22:25]
	v_mfma_f32_16x16x32_bf16 v[18:21], v[110:113], v[196:199], v[18:21]
.Lop_skip3:
	s_setprio 0
	s_barrier
	s_add_u32 s22, s26, 0x40000
	s_addc_u32 s23, s27, 0
	s_add_i32 s50, s51, s31
	v_lshl_add_u64 v[98:99], s[22:23], 0, v[0:1]
	s_mov_b32 m0, s50
	s_nop 0
	global_load_lds_dwordx4 v[98:99], off
	v_lshl_add_u64 v[98:99], s[22:23], 0, v[146:147]
	s_add_i32 m0, s50, 0x2000
	s_nop 0
	global_load_lds_dwordx4 v[98:99], off
	s_waitcnt vmcnt(6)
	s_barrier
	s_setprio 1
	s_cmp_lg_u32 s99, 0
	s_cbranch_scc1 .Lop_skip4
	v_mfma_f32_16x16x32_bf16 v[50:53], v[230:233], v[152:155], v[50:53]
	v_mfma_f32_16x16x32_bf16 v[46:49], v[238:241], v[152:155], v[46:49]
	v_mfma_f32_16x16x32_bf16 v[38:41], v[230:233], v[176:179], v[38:41]
	v_mfma_f32_16x16x32_bf16 v[34:37], v[238:241], v[176:179], v[34:37]
	v_mfma_f32_16x16x32_bf16 v[14:17], v[230:233], v[184:187], v[14:17]
	v_mfma_f32_16x16x32_bf16 v[10:13], v[238:241], v[184:187], v[10:13]
	v_mfma_f32_16x16x32_bf16 v[6:9], v[230:233], v[192:195], v[6:9]
	v_mfma_f32_16x16x32_bf16 v[2:5], v[238:241], v[192:195], v[2:5]
	v_mfma_f32_16x16x32_bf16 v[50:53], v[234:237], v[156:159], v[50:53]
	v_mfma_f32_16x16x32_bf16 v[46:49], v[242:245], v[156:159], v[46:49]
	v_mfma_f32_16x16x32_bf16 v[38:41], v[234:237], v[180:183], v[38:41]
	v_mfma_f32_16x16x32_bf16 v[34:37], v[242:245], v[180:183], v[34:37]
	v_mfma_f32_16x16x32_bf16 v[14:17], v[234:237], v[188:191], v[14:17]
	v_mfma_f32_16x16x32_bf16 v[10:13], v[242:245], v[188:191], v[10:13]
	v_mfma_f32_16x16x32_bf16 v[6:9], v[234:237], v[196:199], v[6:9]
	v_mfma_f32_16x16x32_bf16 v[2:5], v[242:245], v[196:199], v[2:5]
.Lop_skip4:
	s_setprio 0
	s_add_i32 s50, 0, 0x18000
	v_add_u32_e32 v110, s50, v160
	s_barrier
	ds_read_b128 v[98:101], v110
	ds_read_b128 v[102:105], v110 offset:1024
	ds_read_b128 v[106:109], v110 offset:2048
	ds_read_b128 v[110:113], v110 offset:3072
	s_add_u32 s22, s28, 0x40000
	s_addc_u32 s23, s29, 0
	s_mov_b32 m0, s37
	v_lshl_add_u64 v[230:231], s[22:23], 0, v[0:1]
	ds_read_b128 v[152:155], v161 offset:32768
	ds_read_b128 v[156:159], v161 offset:33792
	ds_read_b128 v[176:179], v161 offset:34816
	ds_read_b128 v[180:183], v161 offset:35840
	ds_read_b128 v[184:187], v161 offset:36864
	ds_read_b128 v[188:191], v161 offset:37888
	ds_read_b128 v[192:195], v161 offset:38912
	ds_read_b128 v[196:199], v161 offset:39936
	global_load_lds_dwordx4 v[230:231], off
	v_lshl_add_u64 v[230:231], s[22:23], 0, v[146:147]
	s_mov_b32 m0, s38
	s_nop 0
	global_load_lds_dwordx4 v[230:231], off
	s_waitcnt lgkmcnt(8)
	s_barrier
	s_waitcnt lgkmcnt(0)
	s_setprio 1
	s_waitcnt lgkmcnt(0)
	v_mfma_f32_16x16x32_bf16 v[142:145], v[98:101], v[152:155], v[142:145]
	v_mfma_f32_16x16x32_bf16 v[138:141], v[106:109], v[152:155], v[138:141]
	v_mfma_f32_16x16x32_bf16 v[134:137], v[98:101], v[176:179], v[134:137]
	v_mfma_f32_16x16x32_bf16 v[122:125], v[106:109], v[176:179], v[122:125]
	v_mfma_f32_16x16x32_bf16 v[94:97], v[98:101], v[184:187], v[94:97]
	v_mfma_f32_16x16x32_bf16 v[90:93], v[106:109], v[184:187], v[90:93]
	v_mfma_f32_16x16x32_bf16 v[86:89], v[98:101], v[192:195], v[86:89]
	v_mfma_f32_16x16x32_bf16 v[74:77], v[106:109], v[192:195], v[74:77]
	v_mfma_f32_16x16x32_bf16 v[142:145], v[102:105], v[156:159], v[142:145]
	v_mfma_f32_16x16x32_bf16 v[138:141], v[110:113], v[156:159], v[138:141]
	v_mfma_f32_16x16x32_bf16 v[134:137], v[102:105], v[180:183], v[134:137]
	v_mfma_f32_16x16x32_bf16 v[122:125], v[110:113], v[180:183], v[122:125]
	v_mfma_f32_16x16x32_bf16 v[94:97], v[102:105], v[188:191], v[94:97]
	v_mfma_f32_16x16x32_bf16 v[90:93], v[110:113], v[188:191], v[90:93]
	v_mfma_f32_16x16x32_bf16 v[86:89], v[102:105], v[196:199], v[86:89]
	v_mfma_f32_16x16x32_bf16 v[74:77], v[110:113], v[196:199], v[74:77]
	s_setprio 0
	s_barrier
	s_add_i32 s28, 0, 0x1c000
	s_add_i32 s22, s50, s31
	v_add_u32_e32 v169, s28, v160
	v_lshl_add_u64 v[200:201], v[200:201], 0, s[92:93]
	s_mov_b32 m0, s22
	ds_read_b128 v[230:233], v169
	ds_read_b128 v[234:237], v169 offset:1024
	ds_read_b128 v[238:241], v169 offset:2048
	ds_read_b128 v[242:245], v169 offset:3072
	global_load_lds_dwordx4 v[200:201], off
	v_lshl_add_u64 v[200:201], v[246:247], 0, s[92:93]
	s_add_i32 m0, s22, 0x2000
	s_nop 0
	global_load_lds_dwordx4 v[200:201], off
	s_barrier
	s_waitcnt lgkmcnt(0)
	s_setprio 1
	s_waitcnt lgkmcnt(0)
	v_mfma_f32_16x16x32_bf16 v[130:133], v[230:233], v[152:155], v[130:133]
	v_mfma_f32_16x16x32_bf16 v[126:129], v[238:241], v[152:155], v[126:129]
	v_mfma_f32_16x16x32_bf16 v[118:121], v[230:233], v[176:179], v[118:121]
	v_mfma_f32_16x16x32_bf16 v[114:117], v[238:241], v[176:179], v[114:117]
	v_mfma_f32_16x16x32_bf16 v[82:85], v[230:233], v[184:187], v[82:85]
	v_mfma_f32_16x16x32_bf16 v[78:81], v[238:241], v[184:187], v[78:81]
	v_mfma_f32_16x16x32_bf16 v[70:73], v[230:233], v[192:195], v[70:73]
	v_mfma_f32_16x16x32_bf16 v[66:69], v[238:241], v[192:195], v[66:69]
	v_mfma_f32_16x16x32_bf16 v[130:133], v[234:237], v[156:159], v[130:133]
	v_mfma_f32_16x16x32_bf16 v[126:129], v[242:245], v[156:159], v[126:129]
	v_mfma_f32_16x16x32_bf16 v[118:121], v[234:237], v[180:183], v[118:121]
	v_mfma_f32_16x16x32_bf16 v[114:117], v[242:245], v[180:183], v[114:117]
	v_mfma_f32_16x16x32_bf16 v[82:85], v[234:237], v[188:191], v[82:85]
	v_mfma_f32_16x16x32_bf16 v[78:81], v[242:245], v[188:191], v[78:81]
	v_mfma_f32_16x16x32_bf16 v[70:73], v[234:237], v[196:199], v[70:73]
	v_mfma_f32_16x16x32_bf16 v[66:69], v[242:245], v[196:199], v[66:69]
	s_setprio 0
	s_mov_b32 m0, s41
	v_lshl_add_u64 v[200:201], v[248:249], 0, s[92:93]
	s_barrier
	ds_read_b128 v[152:155], v161 offset:49152
	ds_read_b128 v[156:159], v161 offset:50176
	ds_read_b128 v[176:179], v161 offset:51200
	ds_read_b128 v[180:183], v161 offset:52224
	ds_read_b128 v[184:187], v161 offset:53248
	ds_read_b128 v[188:191], v161 offset:54272
	ds_read_b128 v[192:195], v161 offset:55296
	ds_read_b128 v[196:199], v161 offset:56320
	global_load_lds_dwordx4 v[200:201], off
	v_lshl_add_u64 v[200:201], v[250:251], 0, s[92:93]
	s_mov_b32 m0, s42
	s_nop 0
	global_load_lds_dwordx4 v[200:201], off
	s_barrier
	s_waitcnt lgkmcnt(0)
	s_setprio 1
	s_waitcnt lgkmcnt(0)
	s_cmp_lg_u32 s99, 0
	s_cbranch_scc1 .Lop_skip7
	v_mfma_f32_16x16x32_bf16 v[62:65], v[98:101], v[152:155], v[62:65]
	v_mfma_f32_16x16x32_bf16 v[58:61], v[106:109], v[152:155], v[58:61]
	v_mfma_f32_16x16x32_bf16 v[54:57], v[98:101], v[176:179], v[54:57]
	v_mfma_f32_16x16x32_bf16 v[42:45], v[106:109], v[176:179], v[42:45]
	v_mfma_f32_16x16x32_bf16 v[30:33], v[98:101], v[184:187], v[30:33]
	v_mfma_f32_16x16x32_bf16 v[26:29], v[106:109], v[184:187], v[26:29]
	v_mfma_f32_16x16x32_bf16 v[22:25], v[98:101], v[192:195], v[22:25]
	v_mfma_f32_16x16x32_bf16 v[18:21], v[106:109], v[192:195], v[18:21]
	v_mfma_f32_16x16x32_bf16 v[62:65], v[102:105], v[156:159], v[62:65]
	v_mfma_f32_16x16x32_bf16 v[58:61], v[110:113], v[156:159], v[58:61]
	v_mfma_f32_16x16x32_bf16 v[54:57], v[102:105], v[180:183], v[54:57]
	v_mfma_f32_16x16x32_bf16 v[42:45], v[110:113], v[180:183], v[42:45]
	v_mfma_f32_16x16x32_bf16 v[30:33], v[102:105], v[188:191], v[30:33]
	v_mfma_f32_16x16x32_bf16 v[26:29], v[110:113], v[188:191], v[26:29]
	v_mfma_f32_16x16x32_bf16 v[22:25], v[102:105], v[196:199], v[22:25]
	v_mfma_f32_16x16x32_bf16 v[18:21], v[110:113], v[196:199], v[18:21]
.Lop_skip7:
	s_setprio 0
	s_barrier
	s_add_u32 s22, s26, 0x40080
	s_addc_u32 s23, s27, 0
	s_add_i32 s26, s28, s31
	v_lshl_add_u64 v[98:99], s[22:23], 0, v[0:1]
	s_mov_b32 m0, s26
	s_nop 0
	global_load_lds_dwordx4 v[98:99], off
	v_lshl_add_u64 v[98:99], s[22:23], 0, v[146:147]
	s_add_i32 m0, s26, 0x2000
	s_nop 0
	global_load_lds_dwordx4 v[98:99], off
	s_waitcnt vmcnt(6)
	s_barrier
	s_setprio 1
	s_cmp_lg_u32 s99, 0
	s_cbranch_scc1 .Lop_skip8
	v_mfma_f32_16x16x32_bf16 v[50:53], v[230:233], v[152:155], v[50:53]
	v_mfma_f32_16x16x32_bf16 v[46:49], v[238:241], v[152:155], v[46:49]
	v_mfma_f32_16x16x32_bf16 v[38:41], v[230:233], v[176:179], v[38:41]
	v_mfma_f32_16x16x32_bf16 v[34:37], v[238:241], v[176:179], v[34:37]
	v_mfma_f32_16x16x32_bf16 v[14:17], v[230:233], v[184:187], v[14:17]
	v_mfma_f32_16x16x32_bf16 v[10:13], v[238:241], v[184:187], v[10:13]
	v_mfma_f32_16x16x32_bf16 v[6:9], v[230:233], v[192:195], v[6:9]
	v_mfma_f32_16x16x32_bf16 v[2:5], v[238:241], v[192:195], v[2:5]
	v_mfma_f32_16x16x32_bf16 v[50:53], v[234:237], v[156:159], v[50:53]
	v_mfma_f32_16x16x32_bf16 v[46:49], v[242:245], v[156:159], v[46:49]
	v_mfma_f32_16x16x32_bf16 v[38:41], v[234:237], v[180:183], v[38:41]
	v_mfma_f32_16x16x32_bf16 v[34:37], v[242:245], v[180:183], v[34:37]
	v_mfma_f32_16x16x32_bf16 v[14:17], v[234:237], v[188:191], v[14:17]
	v_mfma_f32_16x16x32_bf16 v[10:13], v[242:245], v[188:191], v[10:13]
	v_mfma_f32_16x16x32_bf16 v[6:9], v[234:237], v[196:199], v[6:9]
	v_mfma_f32_16x16x32_bf16 v[2:5], v[242:245], v[196:199], v[2:5]
.Lop_skip8:
	s_setprio 0
	s_add_i32 s49, s49, 2
	s_add_u32 s47, s47, 0x100
	s_addc_u32 s48, s48, 0
	s_cmp_gt_u32 s49, 13
	s_mov_b64 s[22:23], s[24:25]
	s_barrier
	s_cbranch_scc0 .LBB0_346
	v_mov_b32_e32 v154, v163
	s_lshl_b32 s13, s20, 8
	v_readlane_b32 s98, v254, 0
	s_and_b32 s98, s98, s99
	s_lshl_b32 s98, s98, 7
	s_add_i32 s13, s13, s98
	v_ashrrev_i32_e32 v99, 2, v154
	v_and_b32_e32 v99, 0xffffffc0, v99
	v_add_u32_e32 v155, s13, v99
	s_addk_i32 s13, 0xe000
	s_lshr_b32 s13, s13, 11
	s_lshl_b32 s15, s21, 8
	s_add_i32 s13, s13, 1
	s_cmp_gt_i32 s20, 31
	s_cselect_b64 s[20:21], -1, 0
	v_lshrrev_b32_e32 v99, 1, v154
	s_and_b64 vcc, s[20:21], exec
	v_and_b32_e32 v98, 0xc0, v154
	v_and_b32_e32 v99, 24, v99
	s_cselect_b32 s13, s13, 0
	v_or3_b32 v152, v98, s15, v99
	s_mul_hi_u32 s15, s13, 0x6000
	s_mulk_i32 s13, 0x6000
	s_add_u32 s20, s39, s13
	s_addc_u32 s21, s40, s15
	v_ashrrev_i32_e32 v153, 31, v152
	v_lshl_add_u64 v[106:107], v[152:153], 2, s[20:21]
	global_load_dwordx4 v[102:105], v[106:107], off offset:16
	global_load_dwordx4 v[110:113], v[106:107], off
	global_load_dwordx4 v[98:101], v[106:107], off offset:144
	s_nop 0
	global_load_dwordx4 v[106:109], v[106:107], off offset:128
	v_and_or_b32 v154, v154, 15, v155
	s_mov_b64 s[20:21], -1
	v_ashrrev_i32_e32 v155, 31, v154
	s_cbranch_vccz .LBB0_349
	v_lshlrev_b64 v[158:159], 12, v[154:155]
	s_mov_b32 s20, 0xfe000000
	v_lshl_add_u64 v[156:157], s[6:7], 0, v[158:159]
	s_mov_b32 s21, -1
	v_lshl_add_u64 v[156:157], v[156:157], 0, s[20:21]
	s_mov_b64 s[20:21], 0

.LBB0_356:
	v_readlane_b32 s98, v255, 41
	s_cmp_lg_u32 s98, 0
	s_cselect_b32 s0, 0, s0
	v_readlane_b32 s1, v254, 0
	s_cmp_lt_i32 s1, s0
	s_mov_b64 s[4:5], -1
	s_cbranch_scc1 .LBB0_436
	v_readlane_b32 s1, v254, 0
	s_sub_i32 s2, s1, s0
	v_readlane_b32 s1, v254, 5
	s_sub_i32 s1, s1, s0
	s_cmpk_gt_i32 s2, 0x2bf
	v_mov_b32_e32 v4, v163
	s_cbranch_scc1 .LBB0_396
	v_readlane_b32 s8, v254, 25
	v_readlane_b32 s9, v254, 26
	s_load_dwordx2 s[4:5], s[8:9], 0xe8
	v_readlane_b32 s6, v254, 29
	v_readlane_b32 s7, v254, 30
	s_mul_hi_i32 s3, s6, 0x1600000
	s_mul_i32 s6, s6, 0x1600000
	s_waitcnt lgkmcnt(0)
	s_add_u32 s4, s4, s6
	s_load_dwordx2 s[6:7], s[8:9], 0x118
	v_and_b32_e32 v0, 63, v4
	v_lshlrev_b32_e32 v2, 1, v4
	v_and_b32_e32 v5, 24, v2
	v_lshrrev_b32_e32 v2, 2, v4
	v_lshl_add_u32 v16, v0, 2, 0
	v_lshlrev_b32_e32 v14, 8, v0
	v_lshlrev_b32_e32 v0, 1, v0
	v_and_b32_e32 v15, 4, v2
	s_waitcnt lgkmcnt(0)
	v_lshl_add_u64 v[2:3], s[6:7], 0, v[0:1]
	s_mov_b64 s[6:7], 0x934000
	v_ashrrev_i32_e32 v6, 6, v4
	v_lshl_add_u64 v[2:3], v[2:3], 0, s[6:7]
	s_movk_i32 s6, 0x104
	v_mul_lo_u32 v0, v6, s6
	v_lshlrev_b32_e32 v17, 2, v6
	v_and_b32_e32 v4, 35, v4
	s_addc_u32 s5, s5, s3
	s_lshl_b32 s3, s1, 1
	v_add_u32_e32 v7, 8, v6
	v_add_u32_e32 v8, 16, v6
	v_add_u32_e32 v9, 24, v6
	v_add_u32_e32 v10, 32, v6
	v_add_u32_e32 v11, 40, v6
	v_add_u32_e32 v12, 48, v6
	v_add_u32_e32 v13, 56, v6
	v_add3_u32 v14, v16, v14, v17
	v_or3_b32 v15, v15, v4, v5
	s_lshl_b32 s10, s2, 6
	s_lshl_b32 s11, s1, 7
	v_add_u32_e32 v16, v16, v0
	s_branch .LBB0_360

.LBB0_1246:
	s_add_u32 s41, s16, 0x100
	v_mov_b32_e32 v2, 0
	s_addc_u32 s42, s17, 0
	s_mov_b32 s43, -2
	v_mov_b32_e32 v3, v2
	v_mov_b32_e32 v4, v2
	v_mov_b32_e32 v5, v2
	v_mov_b32_e32 v6, v2
	v_mov_b32_e32 v7, v2
	v_mov_b32_e32 v8, v2
	v_mov_b32_e32 v9, v2
	v_mov_b32_e32 v10, v2
	v_mov_b32_e32 v11, v2
	v_mov_b32_e32 v12, v2
	v_mov_b32_e32 v13, v2
	v_mov_b32_e32 v14, v2
	v_mov_b32_e32 v15, v2
	v_mov_b32_e32 v16, v2
	v_mov_b32_e32 v17, v2
	v_mov_b32_e32 v34, v2
	v_mov_b32_e32 v35, v2
	v_mov_b32_e32 v36, v2
	v_mov_b32_e32 v37, v2
	v_mov_b32_e32 v38, v2
	v_mov_b32_e32 v39, v2
	v_mov_b32_e32 v40, v2
	v_mov_b32_e32 v41, v2
	v_mov_b32_e32 v46, v2
	v_mov_b32_e32 v47, v2
	v_mov_b32_e32 v48, v2
	v_mov_b32_e32 v49, v2
	v_mov_b32_e32 v50, v2
	v_mov_b32_e32 v51, v2
	v_mov_b32_e32 v52, v2
	v_mov_b32_e32 v53, v2
	v_mov_b32_e32 v18, v2
	v_mov_b32_e32 v19, v2
	v_mov_b32_e32 v20, v2
	v_mov_b32_e32 v21, v2
	v_mov_b32_e32 v22, v2
	v_mov_b32_e32 v23, v2
	v_mov_b32_e32 v24, v2
	v_mov_b32_e32 v25, v2
	v_mov_b32_e32 v26, v2
	v_mov_b32_e32 v27, v2
	v_mov_b32_e32 v28, v2
	v_mov_b32_e32 v29, v2
	v_mov_b32_e32 v30, v2
	v_mov_b32_e32 v31, v2
	v_mov_b32_e32 v32, v2
	v_mov_b32_e32 v33, v2
	v_mov_b32_e32 v42, v2
	v_mov_b32_e32 v43, v2
	v_mov_b32_e32 v44, v2
	v_mov_b32_e32 v45, v2
	v_mov_b32_e32 v54, v2
	v_mov_b32_e32 v55, v2
	v_mov_b32_e32 v56, v2
	v_mov_b32_e32 v57, v2
	v_mov_b32_e32 v58, v2
	v_mov_b32_e32 v59, v2
	v_mov_b32_e32 v60, v2
	v_mov_b32_e32 v61, v2
	v_mov_b32_e32 v62, v2
	v_mov_b32_e32 v63, v2
	v_mov_b32_e32 v64, v2
	v_mov_b32_e32 v65, v2
	v_mov_b32_e32 v66, v2
	v_mov_b32_e32 v67, v2
	v_mov_b32_e32 v68, v2
	v_mov_b32_e32 v69, v2
	v_mov_b32_e32 v70, v2
	v_mov_b32_e32 v71, v2
	v_mov_b32_e32 v72, v2
	v_mov_b32_e32 v73, v2
	v_mov_b32_e32 v78, v2
	v_mov_b32_e32 v79, v2
	v_mov_b32_e32 v80, v2
	v_mov_b32_e32 v81, v2
	v_mov_b32_e32 v82, v2
	v_mov_b32_e32 v83, v2
	v_mov_b32_e32 v84, v2
	v_mov_b32_e32 v85, v2
	v_mov_b32_e32 v114, v2
	v_mov_b32_e32 v115, v2
	v_mov_b32_e32 v116, v2
	v_mov_b32_e32 v117, v2
	v_mov_b32_e32 v118, v2
	v_mov_b32_e32 v119, v2
	v_mov_b32_e32 v120, v2
	v_mov_b32_e32 v121, v2
	v_mov_b32_e32 v126, v2
	v_mov_b32_e32 v127, v2
	v_mov_b32_e32 v128, v2
	v_mov_b32_e32 v129, v2
	v_mov_b32_e32 v130, v2
	v_mov_b32_e32 v131, v2
	v_mov_b32_e32 v132, v2
	v_mov_b32_e32 v133, v2
	v_mov_b32_e32 v74, v2
	v_mov_b32_e32 v75, v2
	v_mov_b32_e32 v76, v2
	v_mov_b32_e32 v77, v2
	v_mov_b32_e32 v86, v2
	v_mov_b32_e32 v87, v2
	v_mov_b32_e32 v88, v2
	v_mov_b32_e32 v89, v2
	v_mov_b32_e32 v90, v2
	v_mov_b32_e32 v91, v2
	v_mov_b32_e32 v92, v2
	v_mov_b32_e32 v93, v2
	v_mov_b32_e32 v94, v2
	v_mov_b32_e32 v95, v2
	v_mov_b32_e32 v96, v2
	v_mov_b32_e32 v97, v2
	v_mov_b32_e32 v122, v2
	v_mov_b32_e32 v123, v2
	v_mov_b32_e32 v124, v2
	v_mov_b32_e32 v125, v2
	v_mov_b32_e32 v134, v2
	v_mov_b32_e32 v135, v2
	v_mov_b32_e32 v136, v2
	v_mov_b32_e32 v137, v2
	v_mov_b32_e32 v138, v2
	v_mov_b32_e32 v139, v2
	v_mov_b32_e32 v140, v2
	v_mov_b32_e32 v141, v2
	v_mov_b32_e32 v142, v2
	v_mov_b32_e32 v143, v2
	v_mov_b32_e32 v144, v2
	v_mov_b32_e32 v145, v2
	v_readlane_b32 s99, v255, 41
	s_cmp_eq_u32 s36, 2
	s_cselect_b32 s99, s99, 0
